# v7 plus grid barrier: XCD leader releases followers (XGEN add) before its own L1 invalidate
# baseline (speedup 1.0000x reference)
; __device__ __forceinline__ unsigned xb_ld(unsigned* p)              { return __hip_atomic_load(p, __ATOMIC_RELAXED, __HIP_MEMORY_SCOPE_AGENT); }
; __device__ __forceinline__ unsigned xb_add(unsigned* p, unsigned v) { return __hip_atomic_fetch_add(p, v, __ATOMIC_RELAXED, __HIP_MEMORY_SCOPE_AGENT); }
; #define XB_SPIN(cond, bar) do { unsigned _sp = 0; while (cond) { __builtin_amdgcn_s_sleep(1); \
;     if ((++_sp & 255u) == 0u) { if (xb_ld(&(bar)[XB_TMO])) break; if (_sp > XB_SPIN_CAP) { atomicAdd(&(bar)[XB_TMO], 1u); break; } } } } while (0)
; __device__ __forceinline__ void xcd_barrier(const XcdBarrier& b) {
;     ...
;             __builtin_amdgcn_fence(__ATOMIC_RELEASE, "agent");
;             asm volatile("s_waitcnt vmcnt(0)" ::: "memory");
;             const unsigned og = xb_add(&bar[XB_TOP], 1u);
;             const unsigned tg = og / nx;
;             if (og + 1u == (tg + 1u) * nx) xb_add(&bar[XB_TOPGEN], 1u);
;             else XB_SPIN(xb_ld(&bar[XB_TOPGEN]) == tg, bar);
;             __builtin_amdgcn_fence(__ATOMIC_ACQUIRE, "agent");
;             xb_add(&bar[XB_XGEN(b.x)], 1u);
;             asm volatile("s_waitcnt vmcnt(0)" ::: "memory");
.LBB0_282:
	s_or_b64 exec, exec, s[4:5]
	v_mov_b32_e32 v0, s26
	v_add_co_u32_e32 v0, vcc, 0x2000, v0
	v_mov_b32_e32 v1, s3
	s_nop 0
	v_addc_co_u32_e32 v1, vcc, 0, v1, vcc
	v_mov_b32_e32 v2, 1
	s_waitcnt vmcnt(0) lgkmcnt(0)
	flat_atomic_add v[0:1], v2 offset:1024
	buffer_inv sc1
	s_waitcnt vmcnt(0)

; __device__ __forceinline__ unsigned xb_ld(unsigned* p)              { return __hip_atomic_load(p, __ATOMIC_RELAXED, __HIP_MEMORY_SCOPE_AGENT); }
; __device__ __forceinline__ unsigned xb_add(unsigned* p, unsigned v) { return __hip_atomic_fetch_add(p, v, __ATOMIC_RELAXED, __HIP_MEMORY_SCOPE_AGENT); }
; #define XB_SPIN(cond, bar) do { unsigned _sp = 0; while (cond) { __builtin_amdgcn_s_sleep(1); \
;     if ((++_sp & 255u) == 0u) { if (xb_ld(&(bar)[XB_TMO])) break; if (_sp > XB_SPIN_CAP) { atomicAdd(&(bar)[XB_TMO], 1u); break; } } } } while (0)
; __device__ __forceinline__ void xcd_barrier(const XcdBarrier& b) {
;     ...
;             __builtin_amdgcn_fence(__ATOMIC_RELEASE, "agent");
;             asm volatile("s_waitcnt vmcnt(0)" ::: "memory");
;             const unsigned og = xb_add(&bar[XB_TOP], 1u);
;             const unsigned tg = og / nx;
;             if (og + 1u == (tg + 1u) * nx) xb_add(&bar[XB_TOPGEN], 1u);
;             else XB_SPIN(xb_ld(&bar[XB_TOPGEN]) == tg, bar);
;             __builtin_amdgcn_fence(__ATOMIC_ACQUIRE, "agent");
;             xb_add(&bar[XB_XGEN(b.x)], 1u);
;             asm volatile("s_waitcnt vmcnt(0)" ::: "memory");
.LBB0_284:
	s_or_b64 exec, exec, s[4:5]
	v_mov_b32_e32 v0, s26
	v_add_co_u32_e32 v2, vcc, 0x2000, v0
	v_mov_b32_e32 v0, s2
	s_nop 0
	v_addc_co_u32_e32 v3, vcc, 0, v0, vcc
	s_waitcnt vmcnt(0) lgkmcnt(0)
	flat_atomic_add v[2:3], v242 offset:1024
	buffer_inv sc1
	s_waitcnt vmcnt(0)

; __device__ __forceinline__ unsigned xb_ld(unsigned* p)              { return __hip_atomic_load(p, __ATOMIC_RELAXED, __HIP_MEMORY_SCOPE_AGENT); }
; __device__ __forceinline__ unsigned xb_add(unsigned* p, unsigned v) { return __hip_atomic_fetch_add(p, v, __ATOMIC_RELAXED, __HIP_MEMORY_SCOPE_AGENT); }
; #define XB_SPIN(cond, bar) do { unsigned _sp = 0; while (cond) { __builtin_amdgcn_s_sleep(1); \
;     if ((++_sp & 255u) == 0u) { if (xb_ld(&(bar)[XB_TMO])) break; if (_sp > XB_SPIN_CAP) { atomicAdd(&(bar)[XB_TMO], 1u); break; } } } } while (0)
; __device__ __forceinline__ void xcd_barrier(const XcdBarrier& b) {
;     ...
;             __builtin_amdgcn_fence(__ATOMIC_RELEASE, "agent");
;             asm volatile("s_waitcnt vmcnt(0)" ::: "memory");
;             const unsigned og = xb_add(&bar[XB_TOP], 1u);
;             const unsigned tg = og / nx;
;             if (og + 1u == (tg + 1u) * nx) xb_add(&bar[XB_TOPGEN], 1u);
;             else XB_SPIN(xb_ld(&bar[XB_TOPGEN]) == tg, bar);
;             __builtin_amdgcn_fence(__ATOMIC_ACQUIRE, "agent");
;             xb_add(&bar[XB_XGEN(b.x)], 1u);
;             asm volatile("s_waitcnt vmcnt(0)" ::: "memory");
.LBB0_597:
	s_or_b64 exec, exec, s[6:7]
	v_mov_b32_e32 v0, s26
	v_add_co_u32_e32 v2, vcc, 0x2000, v0
	v_mov_b32_e32 v0, s2
	s_nop 0
	v_addc_co_u32_e32 v3, vcc, 0, v0, vcc
	s_waitcnt vmcnt(0) lgkmcnt(0)
	flat_atomic_add v[2:3], v242 offset:1024
	buffer_inv sc1
	s_waitcnt vmcnt(0)

; __device__ __forceinline__ unsigned xb_ld(unsigned* p)              { return __hip_atomic_load(p, __ATOMIC_RELAXED, __HIP_MEMORY_SCOPE_AGENT); }
; __device__ __forceinline__ unsigned xb_add(unsigned* p, unsigned v) { return __hip_atomic_fetch_add(p, v, __ATOMIC_RELAXED, __HIP_MEMORY_SCOPE_AGENT); }
; #define XB_SPIN(cond, bar) do { unsigned _sp = 0; while (cond) { __builtin_amdgcn_s_sleep(1); \
;     if ((++_sp & 255u) == 0u) { if (xb_ld(&(bar)[XB_TMO])) break; if (_sp > XB_SPIN_CAP) { atomicAdd(&(bar)[XB_TMO], 1u); break; } } } } while (0)
; __device__ __forceinline__ void xcd_barrier(const XcdBarrier& b) {
;     ...
;             __builtin_amdgcn_fence(__ATOMIC_RELEASE, "agent");
;             asm volatile("s_waitcnt vmcnt(0)" ::: "memory");
;             const unsigned og = xb_add(&bar[XB_TOP], 1u);
;             const unsigned tg = og / nx;
;             if (og + 1u == (tg + 1u) * nx) xb_add(&bar[XB_TOPGEN], 1u);
;             else XB_SPIN(xb_ld(&bar[XB_TOPGEN]) == tg, bar);
;             __builtin_amdgcn_fence(__ATOMIC_ACQUIRE, "agent");
;             xb_add(&bar[XB_XGEN(b.x)], 1u);
;             asm volatile("s_waitcnt vmcnt(0)" ::: "memory");
.LBB0_854:
	s_or_b64 exec, exec, s[4:5]
	v_mov_b32_e32 v0, s28
	v_add_co_u32_e32 v2, vcc, 0x2000, v0
	v_mov_b32_e32 v0, s2
	s_nop 0
	v_addc_co_u32_e32 v3, vcc, 0, v0, vcc
	s_waitcnt vmcnt(0) lgkmcnt(0)
	flat_atomic_add v[2:3], v242 offset:1024
	buffer_inv sc1
	s_waitcnt vmcnt(0)
